# batch the 8 serialized ln_row stat loads in 3 GEMM epilogues; issue both loads per iteration in LN-fix / gain-bias LDS staging loops
# speedup vs baseline: 1.0130x; 1.0116x over previous
; __device__ __forceinline__ unsigned cvt_pk_bf16(float lo, float hi) { unsigned r; asm volatile("v_cvt_pk_bf16_f32 %0, %1, %2" : "=v"(r) : "v"(lo), "v"(hi)); return r; }
; #define LAS __attribute__((address_space(3)))
; __global__ void __launch_bounds__(512, 2) mega_fwd(Params P) {
;     ...
;                   { LAS unsigned* CV = (LAS unsigned*)(lds + 131072); for (int i = tid; i < 1024; i += 512) CV[i] = (cvt_pk_bf16(cvk[i], 0.f) & 0xffffu) | (cvt_pk_bf16(cvk[5632 + i], 0.f) << 16);
.LBB0_492:
	v_add_co_u32_e32 v6, vcc, 0xffffa800, v4
	v_add_u32_e32 v0, 0x200, v0
	s_nop 0
	v_addc_co_u32_e32 v7, vcc, -1, v5, vcc
	global_load_dword v6, v[6:7], off
	global_load_dword v7, v[4:5], off
	s_waitcnt vmcnt(0) lgkmcnt(0)
	v_cvt_pk_bf16_f32 v6, v6, v1
	v_and_b32_e32 v6, 0xffff, v6
	v_cmp_lt_i32_e32 vcc, s69, v0
	v_cvt_pk_bf16_f32 v7, v7, v1
	s_or_b64 s[6:7], vcc, s[6:7]
	v_lshl_or_b32 v6, v7, 16, v6
	v_lshl_add_u64 v[4:5], v[4:5], 0, s[42:43]
	ds_write_b32 v3, v6
	v_add_u32_e32 v3, 0x800, v3
	s_andn2_b64 exec, exec, s[6:7]
	s_cbranch_execnz .LBB0_492

; __device__ __forceinline__ float xsum_rows(float v) { return xsum32(xsum16(v)); }
; __device__ __forceinline__ void ln_row(const float* st, int row, int fq, float& rs, float& ms) {
;     f32x2 v = *(const f32x2*)(st + (unsigned)(8 * row + 2 * fq));
;     v.x = xsum_rows(v.x); v.y = xsum_rows(v.y);
;     const float mean = v.x * (1.0f / 1024.0f); const float var = v.y * (1.0f / 1024.0f) - mean * mean;
;     rs = __builtin_amdgcn_rsqf(var + 1e-5f); ms = rs * mean;
; }
;     __device__ __forceinline__ void operator()(const f32x4 (&acc)[2][2][4][2], const Unit& u, int wr, int wc, int fr, int fq, PG8_LAS unsigned char* ldsb) const {
;     ...
;             if (TAG[wr] != u.pm) {
; #pragma unroll
;                 for (int ai = 0; ai < 2; ++ai)
; #pragma unroll
;                     for (int m = 0; m < 4; ++m) { ln_row(ln.st, row0 + ai * HALF + m * 16, fq, rsv[ai][m], msv[ai][m]);
;                         f32x2 pr; pr.x = rsv[ai][m]; pr.y = msv[ai][m]; ST[ai * HALF + wr * 64 + m * 16 + fr] = pr; }
;                 asm volatile("s_waitcnt lgkmcnt(0)" ::: "memory");
;                 TAG[wr] = u.pm;
.LBB0_520:
	v_mov_b32_e32 v0, s47
	ds_read_b32 v0, v0
	v_lshl_add_u32 v158, s52, 8, v161
	s_mov_b64 s[26:27], -1
	s_waitcnt lgkmcnt(0)
	v_cmp_eq_u32_e32 vcc, s52, v0
	s_cbranch_vccnz .LBB0_522
	v_lshlrev_b32_e32 v159, 3, v158
	v_or_b32_e32 v0, v159, v207
	v_lshl_add_u64 v[130:131], v[0:1], 2, s[18:19]
	s_mov_b64 s[26:27], 0
	global_load_dwordx2 v[166:167], v[130:131], off
	global_load_dwordx2 v[168:169], v[130:131], off offset:512
	global_load_dwordx2 v[170:171], v[130:131], off offset:1024
	global_load_dwordx2 v[172:173], v[130:131], off offset:1536
	v_add_u32_e32 v0, v226, v159
	v_lshl_add_u64 v[182:183], v[0:1], 2, s[18:19]
	global_load_dwordx2 v[174:175], v[182:183], off
	global_load_dwordx2 v[176:177], v[182:183], off offset:512
	global_load_dwordx2 v[178:179], v[182:183], off offset:1024
	global_load_dwordx2 v[180:181], v[182:183], off offset:1536
	s_waitcnt vmcnt(0) lgkmcnt(0)
	v_mov_b32_e32 v132, v166
	v_mov_b32_e32 v133, v167
	v_mov_b32_e32 v0, v132
	s_nop 1
	v_permlane16_swap_b32_e32 v132, v0
	v_add_f32_e32 v135, v132, v0
	v_mov_b32_e32 v0, v133
	s_nop 1
	v_permlane16_swap_b32_e32 v133, v0
	v_add_f32_e32 v134, v133, v0
	v_mov_b32_e32 v137, v135
	v_mov_b32_e32 v136, v134
	s_nop 0
	v_permlane32_swap_b32_e32 v135, v137
	v_permlane32_swap_b32_e32 v134, v136
	v_pk_add_f32 v[132:133], v[134:135], v[136:137]
	s_nop 0
	v_pk_mul_f32 v[132:133], v[132:133], s[68:69] op_sel_hi:[1,0]
	s_nop 0
	v_fma_f32 v0, -v133, v133, v132
	v_add_f32_e32 v0, 0x3727c5ac, v0
	v_rsq_f32_e32 v142, v0
	s_nop 0
	v_mul_f32_e32 v143, v133, v142
	ds_write_b64 v209, v[142:143]
	v_mov_b32_e32 v214, v143
	v_mov_b32_e32 v132, v168
	v_mov_b32_e32 v133, v169
	v_mov_b32_e32 v0, v132
	s_nop 1
	v_permlane16_swap_b32_e32 v132, v0
	v_add_f32_e32 v135, v132, v0
	v_mov_b32_e32 v0, v133
	s_nop 1
	v_permlane16_swap_b32_e32 v133, v0
	v_add_f32_e32 v134, v133, v0
	v_mov_b32_e32 v137, v135
	v_mov_b32_e32 v136, v134
	s_nop 0
	v_permlane32_swap_b32_e32 v135, v137
	v_permlane32_swap_b32_e32 v134, v136
	v_pk_add_f32 v[132:133], v[134:135], v[136:137]
	s_nop 0
	v_pk_mul_f32 v[132:133], v[132:133], s[68:69] op_sel_hi:[1,0]
	s_nop 0
	v_fma_f32 v0, -v133, v133, v132
	v_add_f32_e32 v0, 0x3727c5ac, v0
	v_rsq_f32_e32 v144, v0
	s_nop 0
	v_mul_f32_e32 v145, v133, v144
	ds_write_b64 v209, v[144:145] offset:128
	v_mov_b32_e32 v212, v145
	v_mov_b32_e32 v132, v170
	v_mov_b32_e32 v133, v171
	v_mov_b32_e32 v0, v132
	s_nop 1
	v_permlane16_swap_b32_e32 v132, v0
	v_add_f32_e32 v135, v132, v0
	v_mov_b32_e32 v0, v133
	s_nop 1
	v_permlane16_swap_b32_e32 v133, v0
	v_add_f32_e32 v134, v133, v0
	v_mov_b32_e32 v137, v135
	v_mov_b32_e32 v136, v134
	s_nop 0
	v_permlane32_swap_b32_e32 v135, v137
	v_permlane32_swap_b32_e32 v134, v136
	v_pk_add_f32 v[132:133], v[134:135], v[136:137]
	s_nop 0
	v_pk_mul_f32 v[132:133], v[132:133], s[68:69] op_sel_hi:[1,0]
	s_nop 0
	v_fma_f32 v0, -v133, v133, v132
	v_add_f32_e32 v0, 0x3727c5ac, v0
	v_rsq_f32_e32 v138, v0
	s_nop 0
	v_mul_f32_e32 v139, v133, v138
	ds_write_b64 v209, v[138:139] offset:256
	v_mov_b32_e32 v210, v139
	v_mov_b32_e32 v130, v172
	v_mov_b32_e32 v131, v173
	v_mov_b32_e32 v0, v130
	s_nop 1
	v_permlane16_swap_b32_e32 v130, v0
	v_add_f32_e32 v133, v130, v0
	v_mov_b32_e32 v0, v131
	s_nop 1
	v_permlane16_swap_b32_e32 v131, v0
	v_add_f32_e32 v132, v131, v0
	v_mov_b32_e32 v135, v133
	v_mov_b32_e32 v134, v132
	s_nop 0
	v_permlane32_swap_b32_e32 v133, v135
	v_permlane32_swap_b32_e32 v132, v134
	v_pk_add_f32 v[130:131], v[132:133], v[134:135]
	s_nop 0
	v_pk_mul_f32 v[130:131], v[130:131], s[68:69] op_sel_hi:[1,0]
	s_nop 0
	v_fma_f32 v0, -v131, v131, v130
	v_add_f32_e32 v0, 0x3727c5ac, v0
	v_rsq_f32_e32 v140, v0
	v_add_u32_e32 v0, v226, v159
	v_mul_f32_e32 v141, v131, v140
	ds_write_b64 v209, v[140:141] offset:384
	v_lshl_add_u64 v[130:131], v[0:1], 2, s[18:19]
	v_mov_b32_e32 v208, v141
	v_mov_b32_e32 v130, v174
	v_mov_b32_e32 v131, v175
	v_mov_b32_e32 v0, v130
	s_nop 1
	v_permlane16_swap_b32_e32 v130, v0
	v_add_f32_e32 v133, v130, v0
	v_mov_b32_e32 v0, v131
	s_nop 1
	v_permlane16_swap_b32_e32 v131, v0
	v_add_f32_e32 v132, v131, v0
	v_mov_b32_e32 v135, v133
	v_mov_b32_e32 v134, v132
	s_nop 0
	v_permlane32_swap_b32_e32 v133, v135
	v_permlane32_swap_b32_e32 v132, v134
	v_pk_add_f32 v[130:131], v[132:133], v[134:135]
	s_nop 0
	v_pk_mul_f32 v[130:131], v[130:131], s[68:69] op_sel_hi:[1,0]
	s_nop 0
	v_fma_f32 v0, -v131, v131, v130
	v_add_f32_e32 v0, 0x3727c5ac, v0
	v_rsq_f32_e32 v134, v0
	v_add_u32_e32 v0, v227, v159
	v_mul_f32_e32 v135, v131, v134
	ds_write_b64 v209, v[134:135] offset:1024
	v_lshl_add_u64 v[130:131], v[0:1], 2, s[18:19]
	v_mov_b32_e32 v206, v135
	v_mov_b32_e32 v130, v176
	v_mov_b32_e32 v131, v177
	v_mov_b32_e32 v0, v130
	s_nop 1
	v_permlane16_swap_b32_e32 v130, v0
	v_add_f32_e32 v133, v130, v0
	v_mov_b32_e32 v0, v131
	s_nop 1
	v_permlane16_swap_b32_e32 v131, v0
	v_add_f32_e32 v132, v131, v0
	v_mov_b32_e32 v137, v133
	v_mov_b32_e32 v136, v132
	s_nop 0
	v_permlane32_swap_b32_e32 v133, v137
	v_permlane32_swap_b32_e32 v132, v136
	v_pk_add_f32 v[130:131], v[132:133], v[136:137]
	s_nop 0
	v_pk_mul_f32 v[130:131], v[130:131], s[68:69] op_sel_hi:[1,0]
	s_nop 0
	v_fma_f32 v0, -v131, v131, v130
	v_add_f32_e32 v0, 0x3727c5ac, v0
	v_rsq_f32_e32 v136, v0
	v_add_u32_e32 v0, v228, v159
	v_mul_f32_e32 v137, v131, v136
	ds_write_b64 v209, v[136:137] offset:1152
	v_lshl_add_u64 v[130:131], v[0:1], 2, s[18:19]
	v_mov_b32_e32 v204, v137
	v_mov_b32_e32 v130, v178
	v_mov_b32_e32 v131, v179
	v_mov_b32_e32 v0, v130
	s_nop 1
	v_permlane16_swap_b32_e32 v130, v0
	v_add_f32_e32 v133, v130, v0
	v_mov_b32_e32 v0, v131
	s_nop 1
	v_permlane16_swap_b32_e32 v131, v0
	v_add_f32_e32 v132, v131, v0
	v_mov_b32_e32 v163, v133
	v_mov_b32_e32 v162, v132
	s_nop 0
	v_permlane32_swap_b32_e32 v133, v163
	v_permlane32_swap_b32_e32 v132, v162
	v_pk_add_f32 v[130:131], v[132:133], v[162:163]
	s_nop 0
	v_pk_mul_f32 v[130:131], v[130:131], s[68:69] op_sel_hi:[1,0]
	s_nop 0
	v_fma_f32 v0, -v131, v131, v130
	v_add_f32_e32 v0, 0x3727c5ac, v0
	v_rsq_f32_e32 v130, v0
	v_add_u32_e32 v0, v229, v159
	v_lshl_add_u64 v[132:133], v[0:1], 2, s[18:19]
	v_mov_b32_e32 v159, s52
	v_mul_f32_e32 v131, v131, v130
	ds_write_b64 v209, v[130:131] offset:1280
	v_mov_b32_e32 v160, v131
	v_mov_b32_e32 v132, v180
	v_mov_b32_e32 v133, v181
	v_mov_b32_e32 v0, v132
	s_nop 1
	v_permlane16_swap_b32_e32 v132, v0
	v_add_f32_e32 v163, v132, v0
	v_mov_b32_e32 v0, v133
	s_nop 1
	v_permlane16_swap_b32_e32 v133, v0
	v_add_f32_e32 v162, v133, v0
	v_mov_b32_e32 v165, v163
	v_mov_b32_e32 v164, v162
	s_nop 0
	v_permlane32_swap_b32_e32 v163, v165
	v_permlane32_swap_b32_e32 v162, v164
	v_pk_add_f32 v[132:133], v[162:163], v[164:165]
	s_nop 0
	v_pk_mul_f32 v[132:133], v[132:133], s[68:69] op_sel_hi:[1,0]
	s_nop 0
	v_fma_f32 v0, -v133, v133, v132
	v_add_f32_e32 v0, 0x3727c5ac, v0
	v_rsq_f32_e32 v132, v0
	v_mov_b32_e32 v0, s47
	v_mul_f32_e32 v133, v133, v132
	ds_write_b64 v209, v[132:133] offset:1408
	s_waitcnt lgkmcnt(0)
	ds_write_b32 v0, v159
	v_mov_b32_e32 v0, v133

; __device__ __forceinline__ unsigned cvt_pk_bf16(float lo, float hi) { unsigned r; asm volatile("v_cvt_pk_bf16_f32 %0, %1, %2" : "=v"(r) : "v"(lo), "v"(hi)); return r; }
; #define LAS __attribute__((address_space(3)))
; __global__ void __launch_bounds__(512, 2) mega_fwd(Params P) {
;     ...
;                   { LAS unsigned* CV = (LAS unsigned*)(lds + 131072); for (int i = tid; i < nin; i += 512) CV[i] = (cvt_pk_bf16(cvk[i], 0.f) & 0xffffu) | (cvt_pk_bf16(cvk[5632 + i], 0.f) << 16);
.LBB0_648:
	v_add_co_u32_e32 v6, vcc, 0xffffa800, v4
	v_add_u32_e32 v3, 0x200, v3
	s_nop 0
	v_addc_co_u32_e32 v7, vcc, -1, v5, vcc
	global_load_dword v6, v[6:7], off
	global_load_dword v7, v[4:5], off
	s_waitcnt vmcnt(0) lgkmcnt(0)
	v_cvt_pk_bf16_f32 v6, v6, v1
	v_and_b32_e32 v6, 0xffff, v6
	v_cmp_le_i32_e32 vcc, s46, v3
	v_cvt_pk_bf16_f32 v7, v7, v1
	s_or_b64 s[6:7], vcc, s[6:7]
	v_lshl_or_b32 v6, v7, 16, v6
	v_lshl_add_u64 v[4:5], v[4:5], 0, s[42:43]
	ds_write_b32 v0, v6
	v_add_u32_e32 v0, 0x800, v0
	s_andn2_b64 exec, exec, s[6:7]
	s_cbranch_execnz .LBB0_648

; __device__ __forceinline__ float xsum_rows(float v) { return xsum32(xsum16(v)); }
; __device__ __forceinline__ void ln_row(const float* st, int row, int fq, float& rs, float& ms) {
;     f32x2 v = *(const f32x2*)(st + (unsigned)(8 * row + 2 * fq));
;     v.x = xsum_rows(v.x); v.y = xsum_rows(v.y);
;     const float mean = v.x * (1.0f / 1024.0f); const float var = v.y * (1.0f / 1024.0f) - mean * mean;
;     rs = __builtin_amdgcn_rsqf(var + 1e-5f); ms = rs * mean;
; }
;     __device__ __forceinline__ void operator()(const f32x4 (&acc)[2][2][4][2], const Unit& u, int wr, int wc, int fr, int fq, PG8_LAS unsigned char* ldsb) const {
;     ...
;             if (TAG[wr] != u.pm) {
; #pragma unroll
;                 for (int ai = 0; ai < 2; ++ai)
; #pragma unroll
;                     for (int m = 0; m < 4; ++m) { ln_row(ln.st, row0 + ai * HALF + m * 16, fq, rsv[ai][m], msv[ai][m]);
;                         f32x2 pr; pr.x = rsv[ai][m]; pr.y = msv[ai][m]; ST[ai * HALF + wr * 64 + m * 16 + fr] = pr; }
;                 asm volatile("s_waitcnt lgkmcnt(0)" ::: "memory");
;                 TAG[wr] = u.pm;
.LBB0_669:
	v_mov_b32_e32 v0, s47
	ds_read_b32 v0, v0
	v_lshl_add_u32 v230, s53, 8, v159
	s_mov_b64 s[26:27], -1
	s_waitcnt lgkmcnt(0)
	v_cmp_eq_u32_e32 vcc, s53, v0
	s_cbranch_vccnz .LBB0_671
	v_lshlrev_b32_e32 v158, 3, v230
	v_or_b32_e32 v0, v158, v207
	v_lshl_add_u64 v[130:131], v[0:1], 2, s[18:19]
	s_mov_b64 s[26:27], 0
	global_load_dwordx2 v[164:165], v[130:131], off
	global_load_dwordx2 v[166:167], v[130:131], off offset:512
	global_load_dwordx2 v[168:169], v[130:131], off offset:1024
	global_load_dwordx2 v[170:171], v[130:131], off offset:1536
	v_add_u32_e32 v0, v216, v158
	v_lshl_add_u64 v[180:181], v[0:1], 2, s[18:19]
	global_load_dwordx2 v[172:173], v[180:181], off
	global_load_dwordx2 v[174:175], v[180:181], off offset:512
	global_load_dwordx2 v[176:177], v[180:181], off offset:1024
	global_load_dwordx2 v[178:179], v[180:181], off offset:1536
	s_waitcnt vmcnt(0) lgkmcnt(0)
	v_mov_b32_e32 v132, v164
	v_mov_b32_e32 v133, v165
	v_mov_b32_e32 v0, v132
	s_nop 1
	v_permlane16_swap_b32_e32 v132, v0
	v_add_f32_e32 v135, v132, v0
	v_mov_b32_e32 v0, v133
	s_nop 1
	v_permlane16_swap_b32_e32 v133, v0
	v_add_f32_e32 v134, v133, v0
	v_mov_b32_e32 v137, v135
	v_mov_b32_e32 v136, v134
	s_nop 0
	v_permlane32_swap_b32_e32 v135, v137
	v_permlane32_swap_b32_e32 v134, v136
	v_pk_add_f32 v[132:133], v[134:135], v[136:137]
	s_nop 0
	v_pk_mul_f32 v[132:133], v[132:133], s[68:69] op_sel_hi:[1,0]
	s_nop 0
	v_fma_f32 v0, -v133, v133, v132
	v_add_f32_e32 v0, 0x3727c5ac, v0
	v_rsq_f32_e32 v142, v0
	s_nop 0
	v_mul_f32_e32 v143, v133, v142
	ds_write_b64 v209, v[142:143]
	v_mov_b32_e32 v214, v143
	v_mov_b32_e32 v132, v166
	v_mov_b32_e32 v133, v167
	v_mov_b32_e32 v0, v132
	s_nop 1
	v_permlane16_swap_b32_e32 v132, v0
	v_add_f32_e32 v135, v132, v0
	v_mov_b32_e32 v0, v133
	s_nop 1
	v_permlane16_swap_b32_e32 v133, v0
	v_add_f32_e32 v134, v133, v0
	v_mov_b32_e32 v137, v135
	v_mov_b32_e32 v136, v134
	s_nop 0
	v_permlane32_swap_b32_e32 v135, v137
	v_permlane32_swap_b32_e32 v134, v136
	v_pk_add_f32 v[132:133], v[134:135], v[136:137]
	s_nop 0
	v_pk_mul_f32 v[132:133], v[132:133], s[68:69] op_sel_hi:[1,0]
	s_nop 0
	v_fma_f32 v0, -v133, v133, v132
	v_add_f32_e32 v0, 0x3727c5ac, v0
	v_rsq_f32_e32 v144, v0
	s_nop 0
	v_mul_f32_e32 v145, v133, v144
	ds_write_b64 v209, v[144:145] offset:128
	v_mov_b32_e32 v212, v145
	v_mov_b32_e32 v132, v168
	v_mov_b32_e32 v133, v169
	v_mov_b32_e32 v0, v132
	s_nop 1
	v_permlane16_swap_b32_e32 v132, v0
	v_add_f32_e32 v135, v132, v0
	v_mov_b32_e32 v0, v133
	s_nop 1
	v_permlane16_swap_b32_e32 v133, v0
	v_add_f32_e32 v134, v133, v0
	v_mov_b32_e32 v137, v135
	v_mov_b32_e32 v136, v134
	s_nop 0
	v_permlane32_swap_b32_e32 v135, v137
	v_permlane32_swap_b32_e32 v134, v136
	v_pk_add_f32 v[132:133], v[134:135], v[136:137]
	s_nop 0
	v_pk_mul_f32 v[132:133], v[132:133], s[68:69] op_sel_hi:[1,0]
	s_nop 0
	v_fma_f32 v0, -v133, v133, v132
	v_add_f32_e32 v0, 0x3727c5ac, v0
	v_rsq_f32_e32 v138, v0
	s_nop 0
	v_mul_f32_e32 v139, v133, v138
	ds_write_b64 v209, v[138:139] offset:256
	v_mov_b32_e32 v210, v139
	v_mov_b32_e32 v130, v170
	v_mov_b32_e32 v131, v171
	v_mov_b32_e32 v0, v130
	s_nop 1
	v_permlane16_swap_b32_e32 v130, v0
	v_add_f32_e32 v133, v130, v0
	v_mov_b32_e32 v0, v131
	s_nop 1
	v_permlane16_swap_b32_e32 v131, v0
	v_add_f32_e32 v132, v131, v0
	v_mov_b32_e32 v135, v133
	v_mov_b32_e32 v134, v132
	s_nop 0
	v_permlane32_swap_b32_e32 v133, v135
	v_permlane32_swap_b32_e32 v132, v134
	v_pk_add_f32 v[130:131], v[132:133], v[134:135]
	s_nop 0
	v_pk_mul_f32 v[130:131], v[130:131], s[68:69] op_sel_hi:[1,0]
	s_nop 0
	v_fma_f32 v0, -v131, v131, v130
	v_add_f32_e32 v0, 0x3727c5ac, v0
	v_rsq_f32_e32 v140, v0
	v_add_u32_e32 v0, v216, v158
	v_mul_f32_e32 v141, v131, v140
	ds_write_b64 v209, v[140:141] offset:384
	v_lshl_add_u64 v[130:131], v[0:1], 2, s[18:19]
	v_mov_b32_e32 v208, v141
	v_mov_b32_e32 v130, v172
	v_mov_b32_e32 v131, v173
	v_mov_b32_e32 v0, v130
	s_nop 1
	v_permlane16_swap_b32_e32 v130, v0
	v_add_f32_e32 v133, v130, v0
	v_mov_b32_e32 v0, v131
	s_nop 1
	v_permlane16_swap_b32_e32 v131, v0
	v_add_f32_e32 v132, v131, v0
	v_mov_b32_e32 v135, v133
	v_mov_b32_e32 v134, v132
	s_nop 0
	v_permlane32_swap_b32_e32 v133, v135
	v_permlane32_swap_b32_e32 v132, v134
	v_pk_add_f32 v[130:131], v[132:133], v[134:135]
	s_nop 0
	v_pk_mul_f32 v[130:131], v[130:131], s[68:69] op_sel_hi:[1,0]
	s_nop 0
	v_fma_f32 v0, -v131, v131, v130
	v_add_f32_e32 v0, 0x3727c5ac, v0
	v_rsq_f32_e32 v130, v0
	v_add_u32_e32 v0, v217, v158
	v_lshl_add_u64 v[132:133], v[0:1], 2, s[18:19]
	v_mul_f32_e32 v131, v131, v130
	ds_write_b64 v209, v[130:131] offset:1024
	v_mov_b32_e32 v206, v131
	v_mov_b32_e32 v132, v174
	v_mov_b32_e32 v133, v175
	v_mov_b32_e32 v0, v132
	s_nop 1
	v_permlane16_swap_b32_e32 v132, v0
	v_add_f32_e32 v135, v132, v0
	v_mov_b32_e32 v0, v133
	s_nop 1
	v_permlane16_swap_b32_e32 v133, v0
	v_add_f32_e32 v134, v133, v0
	v_mov_b32_e32 v137, v135
	v_mov_b32_e32 v136, v134
	s_nop 0
	v_permlane32_swap_b32_e32 v135, v137
	v_permlane32_swap_b32_e32 v134, v136
	v_pk_add_f32 v[132:133], v[134:135], v[136:137]
	s_nop 0
	v_pk_mul_f32 v[132:133], v[132:133], s[68:69] op_sel_hi:[1,0]
	s_nop 0
	v_fma_f32 v0, -v133, v133, v132
	v_add_f32_e32 v0, 0x3727c5ac, v0
	v_rsq_f32_e32 v132, v0
	v_add_u32_e32 v0, v226, v158
	v_lshl_add_u64 v[134:135], v[0:1], 2, s[18:19]
	v_mul_f32_e32 v133, v133, v132
	ds_write_b64 v209, v[132:133] offset:1152
	v_mov_b32_e32 v200, v133
	v_mov_b32_e32 v134, v176
	v_mov_b32_e32 v135, v177
	v_mov_b32_e32 v0, v134
	s_nop 1
	v_permlane16_swap_b32_e32 v134, v0
	v_add_f32_e32 v137, v134, v0
	v_mov_b32_e32 v0, v135
	s_nop 1
	v_permlane16_swap_b32_e32 v135, v0
	v_add_f32_e32 v136, v135, v0
	v_mov_b32_e32 v161, v137
	v_mov_b32_e32 v160, v136
	s_nop 0
	v_permlane32_swap_b32_e32 v137, v161
	v_permlane32_swap_b32_e32 v136, v160
	v_pk_add_f32 v[134:135], v[136:137], v[160:161]
	s_nop 0
	v_pk_mul_f32 v[134:135], v[134:135], s[68:69] op_sel_hi:[1,0]
	s_nop 0
	v_fma_f32 v0, -v135, v135, v134
	v_add_f32_e32 v0, 0x3727c5ac, v0
	v_rsq_f32_e32 v134, v0
	v_add_u32_e32 v0, v227, v158
	v_lshl_add_u64 v[136:137], v[0:1], 2, s[18:19]
	v_mov_b32_e32 v158, s53
	v_mul_f32_e32 v135, v135, v134
	ds_write_b64 v209, v[134:135] offset:1280
	v_mov_b32_e32 v136, v178
	v_mov_b32_e32 v137, v179
	v_mov_b32_e32 v0, v136
	s_nop 1
	v_permlane16_swap_b32_e32 v136, v0
	v_add_f32_e32 v161, v136, v0
	v_mov_b32_e32 v0, v137
	s_nop 1
	v_permlane16_swap_b32_e32 v137, v0
	v_add_f32_e32 v160, v137, v0
	v_mov_b32_e32 v163, v161
	v_mov_b32_e32 v162, v160
	s_nop 0
	v_permlane32_swap_b32_e32 v161, v163
	v_permlane32_swap_b32_e32 v160, v162
	v_pk_add_f32 v[136:137], v[160:161], v[162:163]
	s_nop 0
	v_pk_mul_f32 v[136:137], v[136:137], s[68:69] op_sel_hi:[1,0]
	s_nop 0
	v_fma_f32 v0, -v137, v137, v136
	v_add_f32_e32 v0, 0x3727c5ac, v0
	v_rsq_f32_e32 v136, v0
	v_mov_b32_e32 v0, s47
	v_mul_f32_e32 v137, v137, v136
	ds_write_b64 v209, v[136:137] offset:1408
	s_waitcnt lgkmcnt(0)
	ds_write_b32 v0, v158
	v_mov_b32_e32 v158, v135
	v_mov_b32_e32 v0, v137

; __device__ __forceinline__ unsigned cvt_pk_bf16(float lo, float hi) { unsigned r; asm volatile("v_cvt_pk_bf16_f32 %0, %1, %2" : "=v"(r) : "v"(lo), "v"(hi)); return r; }
; #define LAS __attribute__((address_space(3)))
; __global__ void __launch_bounds__(512, 2) mega_fwd(Params P) {
;     ...
;                   { LAS unsigned* CV = (LAS unsigned*)(lds + 131072); for (int i = tid; i < 5632; i += 512) CV[i] = (cvt_pk_bf16(cvk[i], 0.f) & 0xffffu) | (cvt_pk_bf16(cvk[5632 + i], 0.f) << 16);
.LBB0_881:
	v_add_co_u32_e32 v6, vcc, 0xffffa800, v4
	v_add_u32_e32 v0, 0x200, v0
	s_nop 0
	v_addc_co_u32_e32 v7, vcc, -1, v5, vcc
	global_load_dword v6, v[6:7], off
	global_load_dword v7, v[4:5], off
	s_waitcnt vmcnt(0) lgkmcnt(0)
	v_cvt_pk_bf16_f32 v6, v6, v1
	s_movk_i32 s8, 0x13ff
	v_and_b32_e32 v6, 0xffff, v6
	v_cmp_lt_i32_e32 vcc, s8, v0
	v_cvt_pk_bf16_f32 v7, v7, v1
	s_or_b64 s[6:7], vcc, s[6:7]
	v_lshl_or_b32 v6, v7, 16, v6
	v_lshl_add_u64 v[4:5], v[4:5], 0, s[42:43]
	ds_write_b32 v3, v6
	v_add_u32_e32 v3, 0x800, v3
	s_andn2_b64 exec, exec, s[6:7]
	s_cbranch_execnz .LBB0_881

; __device__ __forceinline__ void ln_row(const float* st, int row, int fq, float& rs, float& ms) {
;     f32x2 v = *(const f32x2*)(st + (unsigned)(8 * row + 2 * fq));
;     __device__ __forceinline__ void operator()(const f32x4 (&acc)[2][2][4][2], const Unit& u, int wr, int wc, int fr, int fq, PG8_LAS unsigned char* ldsb) const {
;     ...
;         if (TAG[wr] != u.pm) {
; #pragma unroll
;             for (int ai = 0; ai < 2; ++ai)
; #pragma unroll
;                 for (int m = 0; m < 4; ++m) { ln_row(ln.st, row0 + ai * HALF + m * 16, fq, rsv[ai][m], msv[ai][m]);
.LBB0_902:
	v_mov_b32_e32 v0, s49
	ds_read_b32 v0, v0
	v_lshl_add_u32 v168, s61, 8, v167
	s_mov_b64 s[28:29], -1
	v_or_b32_e32 v146, 16, v168
	v_or_b32_e32 v147, 32, v168
	s_waitcnt lgkmcnt(0)
	v_cmp_eq_u32_e32 vcc, s61, v0
	s_and_b64 vcc, exec, vcc
	v_or_b32_e32 v148, 48, v168
	v_add_u32_e32 v149, 0x80, v168
	v_add_u32_e32 v150, 0x90, v168
	v_add_u32_e32 v151, 0xa0, v168
	v_add_u32_e32 v152, 0xb0, v168
	s_cbranch_vccnz .LBB0_904
	v_lshl_or_b32 v0, v168, 3, v197
	v_lshl_add_u64 v[106:107], v[0:1], 2, s[20:21]
	v_or_b32_e32 v217, 16, v168
	v_or_b32_e32 v216, 32, v168
	v_or_b32_e32 v214, 48, v168
	v_add_u32_e32 v212, 0x80, v168
	v_add_u32_e32 v210, 0x90, v168
	v_add_u32_e32 v209, 0xa0, v168
	v_add_u32_e32 v208, 0xb0, v168
	v_mov_b32_e32 v153, s61
	s_mov_b64 s[28:29], 0
	global_load_dwordx2 v[174:175], v[106:107], off
	global_load_dwordx2 v[176:177], v[106:107], off offset:512
	global_load_dwordx2 v[178:179], v[106:107], off offset:1024
	global_load_dwordx2 v[180:181], v[106:107], off offset:1536
	v_lshl_or_b32 v0, v212, 3, v197
	v_lshl_add_u64 v[228:229], v[0:1], 2, s[20:21]
	global_load_dwordx2 v[182:183], v[228:229], off
	global_load_dwordx2 v[204:205], v[228:229], off offset:512
	global_load_dwordx2 v[206:207], v[228:229], off offset:1024
	global_load_dwordx2 v[226:227], v[228:229], off offset:1536
	s_waitcnt vmcnt(0) lgkmcnt(0)
; __device__ __forceinline__ float xsum_rows(float v) { return xsum32(xsum16(v)); }
; __device__ __forceinline__ void ln_row(const float* st, int row, int fq, float& rs, float& ms) {
;     f32x2 v = *(const f32x2*)(st + (unsigned)(8 * row + 2 * fq));
;     v.x = xsum_rows(v.x); v.y = xsum_rows(v.y);
;     const float mean = v.x * (1.0f / 1024.0f); const float var = v.y * (1.0f / 1024.0f) - mean * mean;
;     rs = __builtin_amdgcn_rsqf(var + 1e-5f); ms = rs * mean;
; }
;     __device__ __forceinline__ void operator()(const f32x4 (&acc)[2][2][4][2], const Unit& u, int wr, int wc, int fr, int fq, PG8_LAS unsigned char* ldsb) const {
;     ...
;         if (TAG[wr] != u.pm) {
; #pragma unroll
;             for (int ai = 0; ai < 2; ++ai)
; #pragma unroll
;                 for (int m = 0; m < 4; ++m) { ln_row(ln.st, row0 + ai * HALF + m * 16, fq, rsv[ai][m], msv[ai][m]);
;                     f32x2 pr; pr.x = rsv[ai][m]; pr.y = msv[ai][m]; ST[ai * HALF + wr * 64 + m * 16 + fr] = pr; }
;             asm volatile("s_waitcnt lgkmcnt(0)" ::: "memory");
;             TAG[wr] = u.pm;
	v_mov_b32_e32 v106, v174
	v_mov_b32_e32 v107, v175
	v_mov_b32_e32 v0, v106
	s_nop 1
	v_permlane16_swap_b32_e32 v106, v0
	v_add_f32_e32 v109, v106, v0
	v_mov_b32_e32 v0, v107
	s_nop 1
	v_permlane16_swap_b32_e32 v107, v0
	v_add_f32_e32 v108, v107, v0
	v_mov_b32_e32 v135, v109
	v_mov_b32_e32 v134, v108
	s_nop 0
	v_permlane32_swap_b32_e32 v109, v135
	v_permlane32_swap_b32_e32 v108, v134
	v_pk_add_f32 v[106:107], v[108:109], v[134:135]
	s_nop 0
	v_pk_mul_f32 v[106:107], v[106:107], s[68:69] op_sel_hi:[1,0]
	s_nop 0
	v_fma_f32 v0, -v107, v107, v106
	v_add_f32_e32 v0, 0x3727c5ac, v0
	v_rsq_f32_e32 v142, v0
	v_lshl_or_b32 v0, v217, 3, v197
	v_mul_f32_e32 v143, v107, v142
	ds_write_b64 v199, v[142:143]
	v_lshl_add_u64 v[106:107], v[0:1], 2, s[20:21]
	v_mov_b32_e32 v202, v143
	v_mov_b32_e32 v106, v176
	v_mov_b32_e32 v107, v177
	v_mov_b32_e32 v0, v106
	s_nop 1
	v_permlane16_swap_b32_e32 v106, v0
	v_add_f32_e32 v109, v106, v0
	v_mov_b32_e32 v0, v107
	s_nop 1
	v_permlane16_swap_b32_e32 v107, v0
	v_add_f32_e32 v108, v107, v0
	v_mov_b32_e32 v135, v109
	v_mov_b32_e32 v134, v108
	s_nop 0
	v_permlane32_swap_b32_e32 v109, v135
	v_permlane32_swap_b32_e32 v108, v134
	v_pk_add_f32 v[106:107], v[108:109], v[134:135]
	s_nop 0
	v_pk_mul_f32 v[106:107], v[106:107], s[68:69] op_sel_hi:[1,0]
	s_nop 0
	v_fma_f32 v0, -v107, v107, v106
	v_add_f32_e32 v0, 0x3727c5ac, v0
	v_rsq_f32_e32 v144, v0
	v_lshl_or_b32 v0, v216, 3, v197
	v_mul_f32_e32 v145, v107, v144
	ds_write_b64 v199, v[144:145] offset:128
	v_lshl_add_u64 v[106:107], v[0:1], 2, s[20:21]
	v_mov_b32_e32 v200, v145
	v_mov_b32_e32 v106, v178
	v_mov_b32_e32 v107, v179
	v_mov_b32_e32 v0, v106
	s_nop 1
	v_permlane16_swap_b32_e32 v106, v0
	v_add_f32_e32 v109, v106, v0
	v_mov_b32_e32 v0, v107
	s_nop 1
	v_permlane16_swap_b32_e32 v107, v0
	v_add_f32_e32 v108, v107, v0
	v_mov_b32_e32 v135, v109
	v_mov_b32_e32 v134, v108
	s_nop 0
	v_permlane32_swap_b32_e32 v109, v135
	v_permlane32_swap_b32_e32 v108, v134
	v_pk_add_f32 v[106:107], v[108:109], v[134:135]
	s_nop 0
	v_pk_mul_f32 v[106:107], v[106:107], s[68:69] op_sel_hi:[1,0]
	s_nop 0
	v_fma_f32 v0, -v107, v107, v106
	v_add_f32_e32 v0, 0x3727c5ac, v0
	v_rsq_f32_e32 v138, v0
	v_lshl_or_b32 v0, v214, 3, v197
	v_mul_f32_e32 v139, v107, v138
	ds_write_b64 v199, v[138:139] offset:256
	v_lshl_add_u64 v[106:107], v[0:1], 2, s[20:21]
	v_mov_b32_e32 v198, v139
	v_mov_b32_e32 v106, v180
	v_mov_b32_e32 v107, v181
	v_mov_b32_e32 v0, v106
	s_nop 1
	v_permlane16_swap_b32_e32 v106, v0
	v_add_f32_e32 v109, v106, v0
	v_mov_b32_e32 v0, v107
	s_nop 1
	v_permlane16_swap_b32_e32 v107, v0
	v_add_f32_e32 v108, v107, v0
	v_mov_b32_e32 v135, v109
	v_mov_b32_e32 v134, v108
	s_nop 0
	v_permlane32_swap_b32_e32 v109, v135
	v_permlane32_swap_b32_e32 v108, v134
	v_pk_add_f32 v[106:107], v[108:109], v[134:135]
	s_nop 0
	v_pk_mul_f32 v[106:107], v[106:107], s[68:69] op_sel_hi:[1,0]
	s_nop 0
	v_fma_f32 v0, -v107, v107, v106
	v_add_f32_e32 v0, 0x3727c5ac, v0
	v_rsq_f32_e32 v140, v0
	v_lshl_or_b32 v0, v212, 3, v197
	v_mul_f32_e32 v141, v107, v140
	ds_write_b64 v199, v[140:141] offset:384
	v_lshl_add_u64 v[106:107], v[0:1], 2, s[20:21]
	v_mov_b32_e32 v196, v141
	v_mov_b32_e32 v106, v182
	v_mov_b32_e32 v107, v183
	v_mov_b32_e32 v0, v106
	s_nop 1
	v_permlane16_swap_b32_e32 v106, v0
	v_add_f32_e32 v109, v106, v0
	v_mov_b32_e32 v0, v107
	s_nop 1
	v_permlane16_swap_b32_e32 v107, v0
	v_add_f32_e32 v108, v107, v0
	v_mov_b32_e32 v135, v109
	v_mov_b32_e32 v134, v108
	s_nop 0
	v_permlane32_swap_b32_e32 v109, v135
	v_permlane32_swap_b32_e32 v108, v134
	v_pk_add_f32 v[106:107], v[108:109], v[134:135]
	s_nop 0
	v_pk_mul_f32 v[106:107], v[106:107], s[68:69] op_sel_hi:[1,0]
	s_nop 0
	v_fma_f32 v0, -v107, v107, v106
	v_add_f32_e32 v0, 0x3727c5ac, v0
	v_rsq_f32_e32 v134, v0
	v_lshl_or_b32 v0, v210, 3, v197
	v_mul_f32_e32 v135, v107, v134
	ds_write_b64 v199, v[134:135] offset:1024
	v_lshl_add_u64 v[106:107], v[0:1], 2, s[20:21]
	v_mov_b32_e32 v194, v135
	v_mov_b32_e32 v106, v204
	v_mov_b32_e32 v107, v205
	v_mov_b32_e32 v0, v106
	s_nop 1
	v_permlane16_swap_b32_e32 v106, v0
	v_add_f32_e32 v109, v106, v0
	v_mov_b32_e32 v0, v107
	s_nop 1
	v_permlane16_swap_b32_e32 v107, v0
	v_add_f32_e32 v108, v107, v0
	v_mov_b32_e32 v137, v109
	v_mov_b32_e32 v136, v108
	s_nop 0
	v_permlane32_swap_b32_e32 v109, v137
	v_permlane32_swap_b32_e32 v108, v136
	v_pk_add_f32 v[106:107], v[108:109], v[136:137]
	s_nop 0
	v_pk_mul_f32 v[106:107], v[106:107], s[68:69] op_sel_hi:[1,0]
	s_nop 0
	v_fma_f32 v0, -v107, v107, v106
	v_add_f32_e32 v0, 0x3727c5ac, v0
	v_rsq_f32_e32 v136, v0
	v_lshl_or_b32 v0, v209, 3, v197
	v_mul_f32_e32 v137, v107, v136
	ds_write_b64 v199, v[136:137] offset:1152
	v_lshl_add_u64 v[106:107], v[0:1], 2, s[20:21]
	v_mov_b32_e32 v184, v137
	v_mov_b32_e32 v106, v206
	v_mov_b32_e32 v107, v207
	v_mov_b32_e32 v0, v106
	s_nop 1
	v_permlane16_swap_b32_e32 v106, v0
	v_add_f32_e32 v109, v106, v0
	v_mov_b32_e32 v0, v107
	s_nop 1
	v_permlane16_swap_b32_e32 v107, v0
	v_add_f32_e32 v108, v107, v0
	v_mov_b32_e32 v171, v109
	v_mov_b32_e32 v170, v108
	s_nop 0
	v_permlane32_swap_b32_e32 v109, v171
	v_permlane32_swap_b32_e32 v108, v170
	v_pk_add_f32 v[106:107], v[108:109], v[170:171]
	s_nop 0
	v_pk_mul_f32 v[106:107], v[106:107], s[68:69] op_sel_hi:[1,0]
	s_nop 0
	v_fma_f32 v0, -v107, v107, v106
	v_add_f32_e32 v0, 0x3727c5ac, v0
	v_rsq_f32_e32 v106, v0
	v_lshl_or_b32 v0, v208, 3, v197
	v_lshl_add_u64 v[108:109], v[0:1], 2, s[20:21]
	v_mul_f32_e32 v107, v107, v106
	ds_write_b64 v199, v[106:107] offset:1280
	v_mov_b32_e32 v166, v107
	v_mov_b32_e32 v108, v226
	v_mov_b32_e32 v109, v227
	v_mov_b32_e32 v0, v108
	s_nop 1
	v_permlane16_swap_b32_e32 v108, v0
	v_add_f32_e32 v171, v108, v0
	v_mov_b32_e32 v0, v109
	s_nop 1
	v_permlane16_swap_b32_e32 v109, v0
	v_add_f32_e32 v170, v109, v0
	v_mov_b32_e32 v173, v171
	v_mov_b32_e32 v172, v170
	s_nop 0
	v_permlane32_swap_b32_e32 v171, v173
	v_permlane32_swap_b32_e32 v170, v172
	v_pk_add_f32 v[108:109], v[170:171], v[172:173]
	s_nop 0
	v_pk_mul_f32 v[108:109], v[108:109], s[68:69] op_sel_hi:[1,0]
	s_nop 0
	v_fma_f32 v0, -v109, v109, v108
	v_add_f32_e32 v0, 0x3727c5ac, v0
	v_rsq_f32_e32 v108, v0
	v_mov_b32_e32 v0, s49
	v_mul_f32_e32 v109, v109, v108
	ds_write_b64 v199, v[108:109] offset:1408
	s_waitcnt lgkmcnt(0)
	ds_write_b32 v0, v153
	v_mov_b32_e32 v0, v109

; #define LAS __attribute__((address_space(3)))
; __global__ void __launch_bounds__(512, 2) mega_fwd(Params P) {
;     ...
;               { LAS float* gl = (LAS float*)(lds + 147456); for (int i = tid; i < 1024; i += 512) { gl[i] = gpv[i]; gl[1024 + i] = bpv[i]; } __syncthreads(); }
.LBB0_1167:
	global_load_dword v3, v[6:7], off
	global_load_dword v9, v[4:5], off
	v_add_u32_e32 v8, 0xfffff000, v2
	v_add_u32_e32 v0, 0x200, v0
	v_cmp_lt_i32_e32 vcc, s69, v0
	v_lshl_add_u64 v[6:7], v[6:7], 0, s[42:43]
	s_or_b64 s[14:15], vcc, s[14:15]
	v_lshl_add_u64 v[4:5], v[4:5], 0, s[42:43]
	s_waitcnt vmcnt(0) lgkmcnt(0)
	ds_write_b32 v8, v3
	ds_write_b32 v2, v9
	v_add_u32_e32 v2, 0x800, v2
	s_andn2_b64 exec, exec, s[14:15]
	s_cbranch_execnz .LBB0_1167
